# cooperative-groups grid.sync (layer 0) replaced by a light counter barrier: release, non-returning atomic, sc1 poll, acquire
# speedup vs baseline: 1.0595x; 1.0057x over previous
.LBB0_87:
	v_cndmask_b32_e64 v0, 0, 1, s[8:9]
	v_cmp_ne_u32_e64 s[0:1], 1, v0
	s_andn2_b64 vcc, exec, s[8:9]
	s_nop 0
	v_writelane_b32 v254, s0, 20
	s_nop 1
	v_writelane_b32 v254, s1, 21
	s_cbranch_vccnz .LBB0_99
	s_barrier
	s_mov_b64 s[0:1], exec
	v_readlane_b32 s4, v253, 31
	v_readlane_b32 s5, v253, 32
	s_and_b64 s[4:5], s[0:1], s[4:5]
	s_mov_b64 exec, s[4:5]
	s_cbranch_execz .LBB0_98
	v_readlane_b32 s4, v253, 54
	v_readlane_b32 s5, v253, 55
	buffer_wbl2 sc1
	s_waitcnt vmcnt(0)
	s_sub_u32 s4, s4, 0x3200
	s_subb_u32 s5, s5, 0
	v_mov_b32_e32 v0, 1
	global_atomic_add v195, v0, s[4:5]
.Lgs_spin:
	s_sleep 1
	global_load_dword v1, v195, s[4:5] sc1
	s_waitcnt vmcnt(0)
	v_readfirstlane_b32 s8, v1
	s_cmp_lt_u32 s8, s93
	s_cbranch_scc1 .Lgs_spin
